# hgrn_a unit: 16 serialized 2-byte loads issued up front
# speedup vs baseline: 1.0881x; 1.0071x over previous
.LBB0_269:
	s_lshr_b32 s23, s15, 8
	v_ashrrev_i32_e32 v4, 6, v3
	s_lshl_b32 s13, s23, 12
	s_and_b32 s22, s20, 0xfc0
	s_or_b32 s13, s13, s22
	v_lshlrev_b32_e32 v5, 4, v4
	v_add_u32_e32 v6, s13, v5
	v_mov_b64_e32 v[0:1], s[82:83]
	v_mad_i64_i32 v[0:1], s[24:25], v6, s63, v[0:1]
	s_lshl_b32 s84, s12, 1
	v_lshl_add_u64 v[0:1], v[0:1], 0, s[84:85]
	v_lshlrev_b32_e32 v152, 1, v2
	v_lshl_add_u64 v[0:1], v[0:1], 0, v[152:153]
	v_add_co_u32_e32 v6, vcc, s86, v0
	v_sub_f32_e32 v9, 1.0, v8
	s_nop 0
	v_addc_co_u32_e32 v7, vcc, 0, v1, vcc
	s_mul_i32 s30, s13, 0x1800
	s_add_u32 s28, s82, s30
	s_addc_u32 s29, s83, 0
	s_add_u32 s28, s28, s84
	s_addc_u32 s29, s29, 0
	s_add_u32 s28, s28, s86
	s_addc_u32 s29, s29, 0
	s_add_u32 s28, s28, 0xb00
	s_addc_u32 s29, s29, 0
	v_mul_u32_u24_e32 v97, 0x1800, v5
	v_add_u32_e32 v96, v97, v152
	global_load_ushort v80, v96, s[28:29]
	s_add_u32 s28, s28, 0x1800
	s_addc_u32 s29, s29, 0
	global_load_ushort v81, v96, s[28:29]
	s_add_u32 s28, s28, 0x1800
	s_addc_u32 s29, s29, 0
	global_load_ushort v82, v96, s[28:29]
	s_add_u32 s28, s28, 0x1800
	s_addc_u32 s29, s29, 0
	global_load_ushort v83, v96, s[28:29]
	s_add_u32 s28, s28, 0x1800
	s_addc_u32 s29, s29, 0
	global_load_ushort v84, v96, s[28:29]
	s_add_u32 s28, s28, 0x1800
	s_addc_u32 s29, s29, 0
	global_load_ushort v85, v96, s[28:29]
	s_add_u32 s28, s28, 0x1800
	s_addc_u32 s29, s29, 0
	global_load_ushort v86, v96, s[28:29]
	s_add_u32 s28, s28, 0x1800
	s_addc_u32 s29, s29, 0
	global_load_ushort v87, v96, s[28:29]
	s_add_u32 s28, s28, 0x1800
	s_addc_u32 s29, s29, 0
	global_load_ushort v88, v96, s[28:29]
	s_add_u32 s28, s28, 0x1800
	s_addc_u32 s29, s29, 0
	global_load_ushort v89, v96, s[28:29]
	s_add_u32 s28, s28, 0x1800
	s_addc_u32 s29, s29, 0
	global_load_ushort v90, v96, s[28:29]
	s_add_u32 s28, s28, 0x1800
	s_addc_u32 s29, s29, 0
	global_load_ushort v91, v96, s[28:29]
	s_add_u32 s28, s28, 0x1800
	s_addc_u32 s29, s29, 0
	global_load_ushort v92, v96, s[28:29]
	s_add_u32 s28, s28, 0x1800
	s_addc_u32 s29, s29, 0
	global_load_ushort v93, v96, s[28:29]
	s_add_u32 s28, s28, 0x1800
	s_addc_u32 s29, s29, 0
	global_load_ushort v94, v96, s[28:29]
	s_add_u32 s28, s28, 0x1800
	s_addc_u32 s29, s29, 0
	global_load_ushort v95, v96, s[28:29]
	s_add_u32 s28, s28, 0x1800
	s_addc_u32 s29, s29, 0
	s_waitcnt vmcnt(0)
	v_mov_b32_e32 v6, v80
	s_waitcnt vmcnt(0)
	v_lshlrev_b32_e32 v6, 16, v6
	v_mul_f32_e32 v7, 0xbfb8aa3b, v6
	v_exp_f32_e32 v7, v7
	v_mul_f32_e32 v6, 0x3fb8aa3b, v6
	v_exp_f32_e32 v6, v6
	v_add_f32_e32 v7, 1.0, v7
	v_div_scale_f32 v10, s[12:13], v7, v7, 1.0
	v_rcp_f32_e32 v11, v10
	v_add_f32_e32 v6, 1.0, v6
	v_fma_f32 v12, -v10, v11, 1.0
	v_fmac_f32_e32 v11, v12, v11
	v_div_scale_f32 v12, vcc, 1.0, v7, 1.0
	v_mul_f32_e32 v13, v12, v11
	v_fma_f32 v14, -v10, v13, v12
	v_fmac_f32_e32 v13, v14, v11
	v_fma_f32 v10, -v10, v13, v12
	v_div_fmas_f32 v10, v10, v11, v13
	v_div_fixup_f32 v7, v10, v7, 1.0
	v_div_scale_f32 v10, s[12:13], v6, v6, 1.0
	v_rcp_f32_e32 v11, v10
	s_mov_b32 s12, 0xa952000
	v_fma_f32 v7, v9, v7, v8
	v_max_f32_e32 v7, 0xda24260, v7
	v_fma_f32 v12, -v10, v11, 1.0
	v_fmac_f32_e32 v11, v12, v11
	v_div_scale_f32 v12, vcc, 1.0, v6, 1.0
	v_mul_f32_e32 v13, v12, v11
	v_fma_f32 v14, -v10, v13, v12
	v_fmac_f32_e32 v13, v14, v11
	v_fma_f32 v10, -v10, v13, v12
	v_div_fmas_f32 v10, v10, v11, v13
	v_div_fixup_f32 v6, v10, v6, 1.0
	v_add_co_u32_e32 v10, vcc, s12, v0
	v_log_f32_e32 v7, v7
	s_nop 0
	v_addc_co_u32_e32 v11, vcc, 0, v1, vcc
	v_mov_b32_e32 v10, v81
	v_add_f32_e32 v7, 0, v7
	v_mul_f32_e32 v6, v9, v6
	s_waitcnt vmcnt(0)
	v_lshlrev_b32_e32 v10, 16, v10
	v_mul_f32_e32 v11, 0xbfb8aa3b, v10
	v_exp_f32_e32 v11, v11
	v_mul_f32_e32 v10, 0x3fb8aa3b, v10
	v_exp_f32_e32 v10, v10
	v_add_f32_e32 v11, 1.0, v11
	v_div_scale_f32 v12, s[12:13], v11, v11, 1.0
	v_rcp_f32_e32 v13, v12
	v_add_f32_e32 v10, 1.0, v10
	v_fma_f32 v14, -v12, v13, 1.0
	v_fmac_f32_e32 v13, v14, v13
	v_div_scale_f32 v14, vcc, 1.0, v11, 1.0
	v_mul_f32_e32 v15, v14, v13
	v_fma_f32 v16, -v12, v15, v14
	v_fmac_f32_e32 v15, v16, v13
	v_fma_f32 v12, -v12, v15, v14
	v_div_fmas_f32 v12, v12, v13, v15
	v_div_fixup_f32 v11, v12, v11, 1.0
	v_div_scale_f32 v12, s[12:13], v10, v10, 1.0
	v_rcp_f32_e32 v13, v12
	s_mov_b32 s12, 0xa953000
	v_fma_f32 v11, v9, v11, v8
	v_max_f32_e32 v11, 0xda24260, v11
	v_fma_f32 v14, -v12, v13, 1.0
	v_fmac_f32_e32 v13, v14, v13
	v_div_scale_f32 v14, vcc, 1.0, v10, 1.0
	v_mul_f32_e32 v15, v14, v13
	v_fma_f32 v16, -v12, v15, v14
	v_fmac_f32_e32 v15, v16, v13
	v_fma_f32 v12, -v12, v15, v14
	v_div_fmas_f32 v12, v12, v13, v15
	v_div_fixup_f32 v10, v12, v10, 1.0
	v_add_co_u32_e32 v12, vcc, s12, v0
	v_log_f32_e32 v11, v11
	s_nop 0
	v_addc_co_u32_e32 v13, vcc, 0, v1, vcc
	v_mov_b32_e32 v12, v82
	v_add_f32_e32 v11, v7, v11
	v_mul_f32_e32 v10, v9, v10
	s_waitcnt vmcnt(0)
	v_lshlrev_b32_e32 v12, 16, v12
	v_mul_f32_e32 v13, 0xbfb8aa3b, v12
	v_exp_f32_e32 v13, v13
	v_mul_f32_e32 v12, 0x3fb8aa3b, v12
	v_exp_f32_e32 v12, v12
	v_add_f32_e32 v13, 1.0, v13
	v_div_scale_f32 v14, s[12:13], v13, v13, 1.0
	v_rcp_f32_e32 v15, v14
	v_add_f32_e32 v12, 1.0, v12
	v_fma_f32 v16, -v14, v15, 1.0
	v_fmac_f32_e32 v15, v16, v15
	v_div_scale_f32 v16, vcc, 1.0, v13, 1.0
	v_mul_f32_e32 v17, v16, v15
	v_fma_f32 v18, -v14, v17, v16
	v_fmac_f32_e32 v17, v18, v15
	v_fma_f32 v14, -v14, v17, v16
	v_div_fmas_f32 v14, v14, v15, v17
	v_div_fixup_f32 v13, v14, v13, 1.0
	v_div_scale_f32 v14, s[12:13], v12, v12, 1.0
	v_rcp_f32_e32 v15, v14
	s_mov_b32 s12, 0xa955000
	v_fma_f32 v13, v9, v13, v8
	v_max_f32_e32 v13, 0xda24260, v13
	v_fma_f32 v16, -v14, v15, 1.0
	v_fmac_f32_e32 v15, v16, v15
	v_div_scale_f32 v16, vcc, 1.0, v12, 1.0
	v_mul_f32_e32 v17, v16, v15
	v_fma_f32 v18, -v14, v17, v16
	v_fmac_f32_e32 v17, v18, v15
	v_fma_f32 v14, -v14, v17, v16
	v_div_fmas_f32 v14, v14, v15, v17
	v_div_fixup_f32 v12, v14, v12, 1.0
	v_add_co_u32_e32 v14, vcc, s12, v0
	v_log_f32_e32 v13, v13
	s_nop 0
	v_addc_co_u32_e32 v15, vcc, 0, v1, vcc
	v_mov_b32_e32 v14, v83
	v_add_f32_e32 v13, v11, v13
	v_mul_f32_e32 v12, v9, v12
	s_waitcnt vmcnt(0)
	v_lshlrev_b32_e32 v14, 16, v14
	v_mul_f32_e32 v15, 0xbfb8aa3b, v14
	v_exp_f32_e32 v15, v15
	v_mul_f32_e32 v14, 0x3fb8aa3b, v14
	v_exp_f32_e32 v14, v14
	v_add_f32_e32 v15, 1.0, v15
	v_div_scale_f32 v16, s[12:13], v15, v15, 1.0
	v_rcp_f32_e32 v17, v16
	v_add_f32_e32 v14, 1.0, v14
	v_fma_f32 v18, -v16, v17, 1.0
	v_fmac_f32_e32 v17, v18, v17
	v_div_scale_f32 v18, vcc, 1.0, v15, 1.0
	v_mul_f32_e32 v19, v18, v17
	v_fma_f32 v20, -v16, v19, v18
	v_fmac_f32_e32 v19, v20, v17
	v_fma_f32 v16, -v16, v19, v18
	v_div_fmas_f32 v16, v16, v17, v19
	v_div_fixup_f32 v15, v16, v15, 1.0
	v_div_scale_f32 v16, s[12:13], v14, v14, 1.0
	v_rcp_f32_e32 v17, v16
	s_mov_b32 s12, 0xa956000
	v_fma_f32 v15, v9, v15, v8
	v_max_f32_e32 v15, 0xda24260, v15
	v_fma_f32 v18, -v16, v17, 1.0
	v_fmac_f32_e32 v17, v18, v17
	v_div_scale_f32 v18, vcc, 1.0, v14, 1.0
	v_mul_f32_e32 v19, v18, v17
	v_fma_f32 v20, -v16, v19, v18
	v_fmac_f32_e32 v19, v20, v17
	v_fma_f32 v16, -v16, v19, v18
	v_div_fmas_f32 v16, v16, v17, v19
	v_div_fixup_f32 v14, v16, v14, 1.0
	v_add_co_u32_e32 v16, vcc, s12, v0
	v_log_f32_e32 v15, v15
	s_nop 0
	v_addc_co_u32_e32 v17, vcc, 0, v1, vcc
	v_mov_b32_e32 v16, v84
	v_add_f32_e32 v15, v13, v15
	v_mul_f32_e32 v14, v9, v14
	s_waitcnt vmcnt(0)
	v_lshlrev_b32_e32 v16, 16, v16
	v_mul_f32_e32 v17, 0xbfb8aa3b, v16
	v_exp_f32_e32 v17, v17
	v_mul_f32_e32 v16, 0x3fb8aa3b, v16
	v_exp_f32_e32 v16, v16
	v_add_f32_e32 v17, 1.0, v17
	v_div_scale_f32 v18, s[12:13], v17, v17, 1.0
	v_rcp_f32_e32 v19, v18
	v_add_f32_e32 v16, 1.0, v16
	v_fma_f32 v20, -v18, v19, 1.0
	v_fmac_f32_e32 v19, v20, v19
	v_div_scale_f32 v20, vcc, 1.0, v17, 1.0
	v_mul_f32_e32 v21, v20, v19
	v_fma_f32 v22, -v18, v21, v20
	v_fmac_f32_e32 v21, v22, v19
	v_fma_f32 v18, -v18, v21, v20
	v_div_fmas_f32 v18, v18, v19, v21
	v_div_fixup_f32 v17, v18, v17, 1.0
	v_div_scale_f32 v18, s[12:13], v16, v16, 1.0
	v_rcp_f32_e32 v19, v18
	s_mov_b32 s12, 0xa958000
	v_fma_f32 v17, v9, v17, v8
	v_max_f32_e32 v17, 0xda24260, v17
	v_fma_f32 v20, -v18, v19, 1.0
	v_fmac_f32_e32 v19, v20, v19
	v_div_scale_f32 v20, vcc, 1.0, v16, 1.0
	v_mul_f32_e32 v21, v20, v19
	v_fma_f32 v22, -v18, v21, v20
	v_fmac_f32_e32 v21, v22, v19
	v_fma_f32 v18, -v18, v21, v20
	v_div_fmas_f32 v18, v18, v19, v21
	v_div_fixup_f32 v16, v18, v16, 1.0
	v_add_co_u32_e32 v18, vcc, s12, v0
	v_log_f32_e32 v17, v17
	s_nop 0
	v_addc_co_u32_e32 v19, vcc, 0, v1, vcc
	v_mov_b32_e32 v18, v85
	v_add_f32_e32 v17, v15, v17
	v_mul_f32_e32 v16, v9, v16
	s_waitcnt vmcnt(0)
	v_lshlrev_b32_e32 v18, 16, v18
	v_mul_f32_e32 v19, 0xbfb8aa3b, v18
	v_exp_f32_e32 v19, v19
	v_mul_f32_e32 v18, 0x3fb8aa3b, v18
	v_exp_f32_e32 v18, v18
	v_add_f32_e32 v19, 1.0, v19
	v_div_scale_f32 v20, s[12:13], v19, v19, 1.0
	v_rcp_f32_e32 v21, v20
	v_add_f32_e32 v18, 1.0, v18
	v_fma_f32 v22, -v20, v21, 1.0
	v_fmac_f32_e32 v21, v22, v21
	v_div_scale_f32 v22, vcc, 1.0, v19, 1.0
	v_mul_f32_e32 v23, v22, v21
	v_fma_f32 v24, -v20, v23, v22
	v_fmac_f32_e32 v23, v24, v21
	v_fma_f32 v20, -v20, v23, v22
	v_div_fmas_f32 v20, v20, v21, v23
	v_div_fixup_f32 v19, v20, v19, 1.0
	v_div_scale_f32 v20, s[12:13], v18, v18, 1.0
	v_rcp_f32_e32 v21, v20
	s_mov_b32 s12, 0xa959000
	v_fma_f32 v19, v9, v19, v8
	v_max_f32_e32 v19, 0xda24260, v19
	v_fma_f32 v22, -v20, v21, 1.0
	v_fmac_f32_e32 v21, v22, v21
	v_div_scale_f32 v22, vcc, 1.0, v18, 1.0
	v_mul_f32_e32 v23, v22, v21
	v_fma_f32 v24, -v20, v23, v22
	v_fmac_f32_e32 v23, v24, v21
	v_fma_f32 v20, -v20, v23, v22
	v_div_fmas_f32 v20, v20, v21, v23
	v_div_fixup_f32 v18, v20, v18, 1.0
	v_add_co_u32_e32 v20, vcc, s12, v0
	v_log_f32_e32 v19, v19
	s_nop 0
	v_addc_co_u32_e32 v21, vcc, 0, v1, vcc
	v_mov_b32_e32 v20, v86
	v_add_f32_e32 v19, v17, v19
	v_mul_f32_e32 v18, v9, v18
	s_waitcnt vmcnt(0)
	v_lshlrev_b32_e32 v20, 16, v20
	v_mul_f32_e32 v21, 0xbfb8aa3b, v20
	v_exp_f32_e32 v21, v21
	v_mul_f32_e32 v20, 0x3fb8aa3b, v20
	v_exp_f32_e32 v20, v20
	v_add_f32_e32 v21, 1.0, v21
	v_div_scale_f32 v22, s[12:13], v21, v21, 1.0
	v_rcp_f32_e32 v23, v22
	v_add_f32_e32 v20, 1.0, v20
	v_fma_f32 v24, -v22, v23, 1.0
	v_fmac_f32_e32 v23, v24, v23
	v_div_scale_f32 v24, vcc, 1.0, v21, 1.0
	v_mul_f32_e32 v25, v24, v23
	v_fma_f32 v26, -v22, v25, v24
	v_fmac_f32_e32 v25, v26, v23
	v_fma_f32 v22, -v22, v25, v24
	v_div_fmas_f32 v22, v22, v23, v25
	v_div_fixup_f32 v21, v22, v21, 1.0
	v_div_scale_f32 v22, s[12:13], v20, v20, 1.0
	v_rcp_f32_e32 v23, v22
	s_mov_b32 s12, 0xa95b000
	v_fma_f32 v21, v9, v21, v8
	v_max_f32_e32 v21, 0xda24260, v21
	v_fma_f32 v24, -v22, v23, 1.0
	v_fmac_f32_e32 v23, v24, v23
	v_div_scale_f32 v24, vcc, 1.0, v20, 1.0
	v_mul_f32_e32 v25, v24, v23
	v_fma_f32 v26, -v22, v25, v24
	v_fmac_f32_e32 v25, v26, v23
	v_fma_f32 v22, -v22, v25, v24
	v_div_fmas_f32 v22, v22, v23, v25
	v_div_fixup_f32 v20, v22, v20, 1.0
	v_add_co_u32_e32 v22, vcc, s12, v0
	v_log_f32_e32 v21, v21
	s_nop 0
	v_addc_co_u32_e32 v23, vcc, 0, v1, vcc
	v_mov_b32_e32 v22, v87
	v_add_f32_e32 v21, v19, v21
	v_mul_f32_e32 v20, v9, v20
	s_waitcnt vmcnt(0)
	v_lshlrev_b32_e32 v22, 16, v22
	v_mul_f32_e32 v23, 0xbfb8aa3b, v22
	v_exp_f32_e32 v23, v23
	v_mul_f32_e32 v22, 0x3fb8aa3b, v22
	v_exp_f32_e32 v22, v22
	v_add_f32_e32 v23, 1.0, v23
	v_div_scale_f32 v24, s[12:13], v23, v23, 1.0
	v_rcp_f32_e32 v25, v24
	v_add_f32_e32 v22, 1.0, v22
	v_fma_f32 v26, -v24, v25, 1.0
	v_fmac_f32_e32 v25, v26, v25
	v_div_scale_f32 v26, vcc, 1.0, v23, 1.0
	v_mul_f32_e32 v27, v26, v25
	v_fma_f32 v28, -v24, v27, v26
	v_fmac_f32_e32 v27, v28, v25
	v_fma_f32 v24, -v24, v27, v26
	v_div_fmas_f32 v24, v24, v25, v27
	v_div_fixup_f32 v23, v24, v23, 1.0
	v_div_scale_f32 v24, s[12:13], v22, v22, 1.0
	v_rcp_f32_e32 v25, v24
	s_mov_b32 s12, 0xa95c000
	v_fma_f32 v23, v9, v23, v8
	v_max_f32_e32 v23, 0xda24260, v23
	v_fma_f32 v26, -v24, v25, 1.0
	v_fmac_f32_e32 v25, v26, v25
	v_div_scale_f32 v26, vcc, 1.0, v22, 1.0
	v_mul_f32_e32 v27, v26, v25
	v_fma_f32 v28, -v24, v27, v26
	v_fmac_f32_e32 v27, v28, v25
	v_fma_f32 v24, -v24, v27, v26
	v_div_fmas_f32 v24, v24, v25, v27
	v_div_fixup_f32 v22, v24, v22, 1.0
	v_add_co_u32_e32 v24, vcc, s12, v0
	v_log_f32_e32 v23, v23
	s_nop 0
	v_addc_co_u32_e32 v25, vcc, 0, v1, vcc
	v_mov_b32_e32 v24, v88
	v_add_f32_e32 v23, v21, v23
	v_mul_f32_e32 v22, v9, v22
	s_waitcnt vmcnt(0)
	v_lshlrev_b32_e32 v24, 16, v24
	v_mul_f32_e32 v25, 0xbfb8aa3b, v24
	v_exp_f32_e32 v25, v25
	v_mul_f32_e32 v24, 0x3fb8aa3b, v24
	v_exp_f32_e32 v24, v24
	v_add_f32_e32 v25, 1.0, v25
	v_div_scale_f32 v26, s[12:13], v25, v25, 1.0
	v_rcp_f32_e32 v27, v26
	v_add_f32_e32 v24, 1.0, v24
	v_fma_f32 v28, -v26, v27, 1.0
	v_fmac_f32_e32 v27, v28, v27
	v_div_scale_f32 v28, vcc, 1.0, v25, 1.0
	v_mul_f32_e32 v29, v28, v27
	v_fma_f32 v30, -v26, v29, v28
	v_fmac_f32_e32 v29, v30, v27
	v_fma_f32 v26, -v26, v29, v28
	v_div_fmas_f32 v26, v26, v27, v29
	v_div_fixup_f32 v25, v26, v25, 1.0
	v_div_scale_f32 v26, s[12:13], v24, v24, 1.0
	v_rcp_f32_e32 v27, v26
	s_mov_b32 s12, 0xa95e000
	v_fma_f32 v25, v9, v25, v8
	v_max_f32_e32 v25, 0xda24260, v25
	v_fma_f32 v28, -v26, v27, 1.0
	v_fmac_f32_e32 v27, v28, v27
	v_div_scale_f32 v28, vcc, 1.0, v24, 1.0
	v_mul_f32_e32 v29, v28, v27
	v_fma_f32 v30, -v26, v29, v28
	v_fmac_f32_e32 v29, v30, v27
	v_fma_f32 v26, -v26, v29, v28
	v_div_fmas_f32 v26, v26, v27, v29
	v_div_fixup_f32 v24, v26, v24, 1.0
	v_add_co_u32_e32 v26, vcc, s12, v0
	v_log_f32_e32 v25, v25
	s_nop 0
	v_addc_co_u32_e32 v27, vcc, 0, v1, vcc
	v_mov_b32_e32 v26, v89
	v_add_f32_e32 v25, v23, v25
	v_mul_f32_e32 v24, v9, v24
	s_waitcnt vmcnt(0)
	v_lshlrev_b32_e32 v26, 16, v26
	v_mul_f32_e32 v27, 0xbfb8aa3b, v26
	v_exp_f32_e32 v27, v27
	v_mul_f32_e32 v26, 0x3fb8aa3b, v26
	v_exp_f32_e32 v26, v26
	v_add_f32_e32 v27, 1.0, v27
	v_div_scale_f32 v28, s[12:13], v27, v27, 1.0
	v_rcp_f32_e32 v29, v28
	v_add_f32_e32 v26, 1.0, v26
	v_fma_f32 v30, -v28, v29, 1.0
	v_fmac_f32_e32 v29, v30, v29
	v_div_scale_f32 v30, vcc, 1.0, v27, 1.0
	v_mul_f32_e32 v31, v30, v29
	v_fma_f32 v32, -v28, v31, v30
	v_fmac_f32_e32 v31, v32, v29
	v_fma_f32 v28, -v28, v31, v30
	v_div_fmas_f32 v28, v28, v29, v31
	v_div_fixup_f32 v27, v28, v27, 1.0
	v_div_scale_f32 v28, s[12:13], v26, v26, 1.0
	v_rcp_f32_e32 v29, v28
	s_mov_b32 s12, 0xa95f000
	v_fma_f32 v27, v9, v27, v8
	v_max_f32_e32 v27, 0xda24260, v27
	v_fma_f32 v30, -v28, v29, 1.0
	v_fmac_f32_e32 v29, v30, v29
	v_div_scale_f32 v30, vcc, 1.0, v26, 1.0
	v_mul_f32_e32 v31, v30, v29
	v_fma_f32 v32, -v28, v31, v30
	v_fmac_f32_e32 v31, v32, v29
	v_fma_f32 v28, -v28, v31, v30
	v_div_fmas_f32 v28, v28, v29, v31
	v_div_fixup_f32 v26, v28, v26, 1.0
	v_add_co_u32_e32 v28, vcc, s12, v0
	v_log_f32_e32 v27, v27
	s_nop 0
	v_addc_co_u32_e32 v29, vcc, 0, v1, vcc
	v_mov_b32_e32 v28, v90
	v_add_f32_e32 v27, v25, v27
	v_mul_f32_e32 v26, v9, v26
	s_waitcnt vmcnt(0)
	v_lshlrev_b32_e32 v28, 16, v28
	v_mul_f32_e32 v29, 0xbfb8aa3b, v28
	v_exp_f32_e32 v29, v29
	v_mul_f32_e32 v28, 0x3fb8aa3b, v28
	v_exp_f32_e32 v28, v28
	v_add_f32_e32 v29, 1.0, v29
	v_div_scale_f32 v30, s[12:13], v29, v29, 1.0
	v_rcp_f32_e32 v31, v30
	v_add_f32_e32 v28, 1.0, v28
	v_fma_f32 v32, -v30, v31, 1.0
	v_fmac_f32_e32 v31, v32, v31
	v_div_scale_f32 v32, vcc, 1.0, v29, 1.0
	v_mul_f32_e32 v33, v32, v31
	v_fma_f32 v34, -v30, v33, v32
	v_fmac_f32_e32 v33, v34, v31
	v_fma_f32 v30, -v30, v33, v32
	v_div_fmas_f32 v30, v30, v31, v33
	v_div_fixup_f32 v29, v30, v29, 1.0
	v_div_scale_f32 v30, s[12:13], v28, v28, 1.0
	v_rcp_f32_e32 v31, v30
	s_mov_b32 s12, 0xa961000
	v_fma_f32 v29, v9, v29, v8
	v_max_f32_e32 v29, 0xda24260, v29
	v_fma_f32 v32, -v30, v31, 1.0
	v_fmac_f32_e32 v31, v32, v31
	v_div_scale_f32 v32, vcc, 1.0, v28, 1.0
	v_mul_f32_e32 v33, v32, v31
	v_fma_f32 v34, -v30, v33, v32
	v_fmac_f32_e32 v33, v34, v31
	v_fma_f32 v30, -v30, v33, v32
	v_div_fmas_f32 v30, v30, v31, v33
	v_div_fixup_f32 v28, v30, v28, 1.0
	v_add_co_u32_e32 v30, vcc, s12, v0
	v_log_f32_e32 v29, v29
	s_nop 0
	v_addc_co_u32_e32 v31, vcc, 0, v1, vcc
	v_mov_b32_e32 v30, v91
	v_add_f32_e32 v29, v27, v29
	v_mul_f32_e32 v28, v9, v28
	s_waitcnt vmcnt(0)
	v_lshlrev_b32_e32 v30, 16, v30
	v_mul_f32_e32 v31, 0xbfb8aa3b, v30
	v_exp_f32_e32 v31, v31
	v_mul_f32_e32 v30, 0x3fb8aa3b, v30
	v_exp_f32_e32 v30, v30
	v_add_f32_e32 v31, 1.0, v31
	v_div_scale_f32 v32, s[12:13], v31, v31, 1.0
	v_rcp_f32_e32 v33, v32
	v_add_f32_e32 v30, 1.0, v30
	v_fma_f32 v34, -v32, v33, 1.0
	v_fmac_f32_e32 v33, v34, v33
	v_div_scale_f32 v34, vcc, 1.0, v31, 1.0
	v_mul_f32_e32 v35, v34, v33
	v_fma_f32 v36, -v32, v35, v34
	v_fmac_f32_e32 v35, v36, v33
	v_fma_f32 v32, -v32, v35, v34
	v_div_fmas_f32 v32, v32, v33, v35
	v_div_fixup_f32 v31, v32, v31, 1.0
	v_div_scale_f32 v32, s[12:13], v30, v30, 1.0
	v_rcp_f32_e32 v33, v32
	s_mov_b32 s12, 0xa962000
	v_fma_f32 v31, v9, v31, v8
	v_max_f32_e32 v31, 0xda24260, v31
	v_fma_f32 v34, -v32, v33, 1.0
	v_fmac_f32_e32 v33, v34, v33
	v_div_scale_f32 v34, vcc, 1.0, v30, 1.0
	v_mul_f32_e32 v35, v34, v33
	v_fma_f32 v36, -v32, v35, v34
	v_fmac_f32_e32 v35, v36, v33
	v_fma_f32 v32, -v32, v35, v34
	v_div_fmas_f32 v32, v32, v33, v35
	v_div_fixup_f32 v30, v32, v30, 1.0
	v_add_co_u32_e32 v32, vcc, s12, v0
	v_log_f32_e32 v31, v31
	s_nop 0
	v_addc_co_u32_e32 v33, vcc, 0, v1, vcc
	v_mov_b32_e32 v32, v92
	v_add_f32_e32 v31, v29, v31
	v_mul_f32_e32 v30, v9, v30
	s_waitcnt vmcnt(0)
	v_lshlrev_b32_e32 v32, 16, v32
	v_mul_f32_e32 v33, 0xbfb8aa3b, v32
	v_exp_f32_e32 v33, v33
	v_mul_f32_e32 v32, 0x3fb8aa3b, v32
	v_exp_f32_e32 v32, v32
	v_add_f32_e32 v33, 1.0, v33
	v_div_scale_f32 v34, s[12:13], v33, v33, 1.0
	v_rcp_f32_e32 v35, v34
	v_add_f32_e32 v32, 1.0, v32
	v_fma_f32 v36, -v34, v35, 1.0
	v_fmac_f32_e32 v35, v36, v35
	v_div_scale_f32 v36, vcc, 1.0, v33, 1.0
	v_mul_f32_e32 v37, v36, v35
	v_fma_f32 v38, -v34, v37, v36
	v_fmac_f32_e32 v37, v38, v35
	v_fma_f32 v34, -v34, v37, v36
	v_div_fmas_f32 v34, v34, v35, v37
	v_div_fixup_f32 v33, v34, v33, 1.0
	v_div_scale_f32 v34, s[12:13], v32, v32, 1.0
	v_rcp_f32_e32 v35, v34
	s_mov_b32 s12, 0xa964000
	v_fma_f32 v33, v9, v33, v8
	v_max_f32_e32 v33, 0xda24260, v33
	v_fma_f32 v36, -v34, v35, 1.0
	v_fmac_f32_e32 v35, v36, v35
	v_div_scale_f32 v36, vcc, 1.0, v32, 1.0
	v_mul_f32_e32 v37, v36, v35
	v_fma_f32 v38, -v34, v37, v36
	v_fmac_f32_e32 v37, v38, v35
	v_fma_f32 v34, -v34, v37, v36
	v_div_fmas_f32 v34, v34, v35, v37
	v_div_fixup_f32 v32, v34, v32, 1.0
	v_add_co_u32_e32 v34, vcc, s12, v0
	v_log_f32_e32 v33, v33
	s_nop 0
	v_addc_co_u32_e32 v35, vcc, 0, v1, vcc
	v_mov_b32_e32 v34, v93
	v_add_f32_e32 v33, v31, v33
	v_mul_f32_e32 v32, v9, v32
	s_waitcnt vmcnt(0)
	v_lshlrev_b32_e32 v34, 16, v34
	v_mul_f32_e32 v35, 0xbfb8aa3b, v34
	v_exp_f32_e32 v35, v35
	v_mul_f32_e32 v34, 0x3fb8aa3b, v34
	v_exp_f32_e32 v34, v34
	v_add_f32_e32 v35, 1.0, v35
	v_div_scale_f32 v36, s[12:13], v35, v35, 1.0
	v_rcp_f32_e32 v37, v36
	v_add_f32_e32 v34, 1.0, v34
	v_fma_f32 v38, -v36, v37, 1.0
	v_fmac_f32_e32 v37, v38, v37
	v_div_scale_f32 v38, vcc, 1.0, v35, 1.0
	v_mul_f32_e32 v39, v38, v37
	v_fma_f32 v40, -v36, v39, v38
	v_fmac_f32_e32 v39, v40, v37
	v_fma_f32 v36, -v36, v39, v38
	v_div_fmas_f32 v36, v36, v37, v39
	v_div_fixup_f32 v35, v36, v35, 1.0
	v_div_scale_f32 v36, s[12:13], v34, v34, 1.0
	v_rcp_f32_e32 v37, v36
	s_mov_b32 s12, 0xa965000
	v_fma_f32 v35, v9, v35, v8
	v_max_f32_e32 v35, 0xda24260, v35
	v_fma_f32 v38, -v36, v37, 1.0
	v_fmac_f32_e32 v37, v38, v37
	v_div_scale_f32 v38, vcc, 1.0, v34, 1.0
	v_mul_f32_e32 v39, v38, v37
	v_fma_f32 v40, -v36, v39, v38
	v_fmac_f32_e32 v39, v40, v37
	v_fma_f32 v36, -v36, v39, v38
	v_div_fmas_f32 v36, v36, v37, v39
	v_div_fixup_f32 v34, v36, v34, 1.0
	v_add_co_u32_e32 v36, vcc, s12, v0
	v_log_f32_e32 v35, v35
	s_nop 0
	v_addc_co_u32_e32 v37, vcc, 0, v1, vcc
	v_mov_b32_e32 v36, v94
	v_add_f32_e32 v35, v33, v35
	v_mul_f32_e32 v34, v9, v34
	s_waitcnt vmcnt(0)
	v_lshlrev_b32_e32 v36, 16, v36
	v_mul_f32_e32 v37, 0xbfb8aa3b, v36
	v_exp_f32_e32 v37, v37
	v_mul_f32_e32 v36, 0x3fb8aa3b, v36
	v_exp_f32_e32 v36, v36
	v_add_f32_e32 v37, 1.0, v37
	v_div_scale_f32 v38, s[12:13], v37, v37, 1.0
	v_rcp_f32_e32 v39, v38
	v_add_f32_e32 v36, 1.0, v36
	v_fma_f32 v40, -v38, v39, 1.0
	v_fmac_f32_e32 v39, v40, v39
	v_div_scale_f32 v40, vcc, 1.0, v37, 1.0
	v_mul_f32_e32 v41, v40, v39
	v_fma_f32 v42, -v38, v41, v40
	v_fmac_f32_e32 v41, v42, v39
	v_fma_f32 v38, -v38, v41, v40
	v_div_fmas_f32 v38, v38, v39, v41
	v_div_fixup_f32 v37, v38, v37, 1.0
	v_div_scale_f32 v38, s[12:13], v36, v36, 1.0
	v_rcp_f32_e32 v39, v38
	s_mov_b32 s12, 0xa967000
	v_fma_f32 v37, v9, v37, v8
	v_max_f32_e32 v37, 0xda24260, v37
	v_fma_f32 v40, -v38, v39, 1.0
	v_fmac_f32_e32 v39, v40, v39
	v_div_scale_f32 v40, vcc, 1.0, v36, 1.0
	v_mul_f32_e32 v41, v40, v39
	v_fma_f32 v42, -v38, v41, v40
	v_fmac_f32_e32 v41, v42, v39
	v_fma_f32 v38, -v38, v41, v40
	v_div_fmas_f32 v38, v38, v39, v41
	v_add_co_u32_e32 v0, vcc, s12, v0
	v_div_fixup_f32 v36, v38, v36, 1.0
	s_nop 0
	v_addc_co_u32_e32 v1, vcc, 0, v1, vcc
	v_mov_b32_e32 v0, v95
	v_log_f32_e32 v37, v37
	v_mul_f32_e32 v36, v9, v36
	v_add_f32_e32 v37, v35, v37
	s_waitcnt vmcnt(0)
	v_lshlrev_b32_e32 v0, 16, v0
	v_mul_f32_e32 v1, 0xbfb8aa3b, v0
	v_exp_f32_e32 v1, v1
	v_mul_f32_e32 v0, 0x3fb8aa3b, v0
	v_exp_f32_e32 v0, v0
	v_add_f32_e32 v1, 1.0, v1
	v_div_scale_f32 v38, s[12:13], v1, v1, 1.0
	v_rcp_f32_e32 v39, v38
	v_add_f32_e32 v0, 1.0, v0
	v_fma_f32 v40, -v38, v39, 1.0
	v_fmac_f32_e32 v39, v40, v39
	v_div_scale_f32 v40, vcc, 1.0, v1, 1.0
	v_mul_f32_e32 v41, v40, v39
	v_fma_f32 v42, -v38, v41, v40
	v_fmac_f32_e32 v41, v42, v39
	v_fma_f32 v38, -v38, v41, v40
	v_div_fmas_f32 v38, v38, v39, v41
	v_div_fixup_f32 v1, v38, v1, 1.0
	v_div_scale_f32 v38, s[12:13], v0, v0, 1.0
	v_rcp_f32_e32 v39, v38
	v_fmac_f32_e32 v8, v9, v1
	v_max_f32_e32 v1, 0xda24260, v8
	v_log_f32_e32 v1, v1
	v_fma_f32 v40, -v38, v39, 1.0
	v_fmac_f32_e32 v39, v40, v39
	v_div_scale_f32 v40, vcc, 1.0, v0, 1.0
	v_mul_f32_e32 v41, v40, v39
	v_fma_f32 v42, -v38, v41, v40
	v_fmac_f32_e32 v41, v42, v39
	v_fma_f32 v38, -v38, v41, v40
	v_div_fmas_f32 v38, v38, v39, v41
	v_div_fixup_f32 v0, v38, v0, 1.0
	v_add_f32_e32 v38, v37, v1
	v_mul_f32_e32 v39, v9, v0
	v_lshlrev_b32_e32 v0, 2, v3
	v_lshlrev_b32_e32 v40, 2, v2
	ds_write_b32 v0, v38
	s_waitcnt lgkmcnt(0)
	s_barrier
	ds_read2st64_b32 v[0:1], v40 offset1:1
	v_cmp_lt_i32_e32 vcc, 0, v4
	s_waitcnt lgkmcnt(0)
	v_add_f32_e32 v0, 0, v0
	v_cndmask_b32_e32 v8, 0, v0, vcc
	v_add_f32_e32 v9, v0, v1
	v_cmp_lt_i32_e32 vcc, 1, v4
	v_add_f32_e32 v0, v1, v8
	s_nop 0
	v_cndmask_b32_e32 v8, v8, v0, vcc
	ds_read2st64_b32 v[0:1], v40 offset0:2 offset1:3
	v_cmp_lt_i32_e32 vcc, 2, v4
	s_waitcnt lgkmcnt(0)
	v_add_f32_e32 v9, v9, v0
	v_add_f32_e32 v0, v0, v8
	v_cndmask_b32_e32 v8, v8, v0, vcc
	v_add_f32_e32 v0, v9, v1
	v_cmp_lt_i32_e32 vcc, 3, v4
	v_add_f32_e32 v1, v1, v8
	s_nop 0
	v_cndmask_b32_e32 v1, v8, v1, vcc
	v_add_f32_e32 v7, v7, v1
	v_sub_f32_e32 v7, v0, v7
	v_exp_f32_e32 v7, v7
	v_add_f32_e32 v8, v15, v1
	v_sub_f32_e32 v8, v0, v8
	v_exp_f32_e32 v8, v8
	v_mul_f32_e32 v6, v6, v7
	v_add_f32_e32 v7, v11, v1
	v_sub_f32_e32 v7, v0, v7
	v_exp_f32_e32 v7, v7
	v_mul_f32_e32 v8, v14, v8
	v_add_f32_e32 v9, v19, v1
	v_sub_f32_e32 v9, v0, v9
	v_mul_f32_e32 v7, v10, v7
	v_cvt_pk_bf16_f32 v6, v6, v7
	v_add_f32_e32 v7, v13, v1
	v_sub_f32_e32 v7, v0, v7
	v_exp_f32_e32 v7, v7
	v_exp_f32_e32 v9, v9
	v_add_f32_e32 v10, v23, v1
	v_sub_f32_e32 v10, v0, v10
	v_mul_f32_e32 v7, v12, v7
	v_cvt_pk_bf16_f32 v7, v7, v8
	v_add_f32_e32 v8, v17, v1
	v_sub_f32_e32 v8, v0, v8
	v_exp_f32_e32 v8, v8
	v_mul_f32_e32 v9, v18, v9
	v_exp_f32_e32 v10, v10
	v_add_f32_e32 v11, v27, v1
	v_mul_f32_e32 v8, v16, v8
	v_cvt_pk_bf16_f32 v8, v8, v9
	v_add_f32_e32 v9, v21, v1
	v_sub_f32_e32 v9, v0, v9
	v_exp_f32_e32 v9, v9
	v_mul_f32_e32 v10, v22, v10
	v_sub_f32_e32 v11, v0, v11
	v_exp_f32_e32 v11, v11
	v_mul_f32_e32 v9, v20, v9
	v_cvt_pk_bf16_f32 v9, v9, v10
	v_add_f32_e32 v10, v25, v1
	v_sub_f32_e32 v10, v0, v10
	v_exp_f32_e32 v10, v10
	v_mul_f32_e32 v11, v26, v11
	v_add_f32_e32 v12, v31, v1
	v_sub_f32_e32 v12, v0, v12
	v_mul_f32_e32 v10, v24, v10
	v_cvt_pk_bf16_f32 v10, v10, v11
	v_add_f32_e32 v11, v29, v1
	v_sub_f32_e32 v11, v0, v11
	v_exp_f32_e32 v11, v11
	v_exp_f32_e32 v12, v12
	v_add_f32_e32 v13, v35, v1
	v_sub_f32_e32 v13, v0, v13
	v_mul_f32_e32 v11, v28, v11
	v_mul_f32_e32 v12, v30, v12
	v_cvt_pk_bf16_f32 v11, v11, v12
	v_add_f32_e32 v12, v33, v1
	v_sub_f32_e32 v12, v0, v12
	v_exp_f32_e32 v12, v12
	v_exp_f32_e32 v13, v13
	v_lshlrev_b32_e32 v14, 5, v4
	v_cmp_gt_u32_e32 vcc, 64, v3
	v_mul_f32_e32 v12, v32, v12
	v_mul_f32_e32 v13, v34, v13
	v_cvt_pk_bf16_f32 v12, v12, v13
	v_add_f32_e32 v13, v37, v1
	v_add_f32_e32 v1, v38, v1
	v_sub_f32_e32 v13, v0, v13
	v_sub_f32_e32 v1, v0, v1
	v_exp_f32_e32 v13, v13
	v_exp_f32_e32 v1, v1
	v_mul_f32_e32 v13, v36, v13
	v_mul_f32_e32 v1, v39, v1
	v_cvt_pk_bf16_f32 v13, v13, v1
	v_mul_u32_u24_e32 v1, 0x8c, v2
	v_add3_u32 v1, v40, v1, v14
	ds_write_b128 v1, v[6:9] offset:1024
	ds_write_b128 v1, v[10:13] offset:1040
	s_and_saveexec_b64 s[12:13], vcc
	s_cbranch_execz .LBB0_266
	v_exp_f32_e32 v6, v0
	v_add_u32_e32 v152, s20, v3
	v_lshl_add_u64 v[0:1], v[152:153], 2, s[2:3]
	global_store_dword v[0:1], v6, off
	s_branch .LBB0_266
